# full stack plus phase-6 half-tile epilogue loads in K stage 14 and phase-4 section order swapped for workgroups 256..511
# speedup vs baseline: 1.0223x; 1.0047x over previous
.LBB0_730:
	s_or_b64 exec, exec, s[0:1]
	s_abs_i32 s0, s52
	v_cvt_f32_u32_e32 v2, s0
	s_sub_i32 s1, 0, s0
	v_readlane_b32 s60, v236, 3
	v_readlane_b32 s61, v236, 4
	v_rcp_iflag_f32_e32 v2, v2
	s_barrier
	v_mul_f32_e32 v2, 0x4f7ffffe, v2
	v_cvt_u32_f32_e32 v2, v2
	s_nop 0
	v_readfirstlane_b32 s2, v2
	s_mul_i32 s1, s1, s2
	s_mul_hi_u32 s1, s2, s1
	s_add_i32 s2, s2, s1
	s_mul_hi_u32 s1, s2, 0x220
	s_mul_i32 s1, s1, s0
	s_sub_i32 s1, 0x220, s1
	s_sub_i32 s2, s1, s0
	s_cmp_ge_u32 s1, s0
	s_cselect_b32 s1, s2, s1
	s_sub_i32 s2, s1, s0
	s_cmp_ge_u32 s1, s0
	s_cselect_b32 s17, s2, s1
	s_sub_i32 s18, 0x220, s17
	s_lshl_b32 s16, s17, 1
	s_cmp_le_i32 s16, s52
	s_cselect_b32 s19, s16, 0
	s_cmp_eq_u32 s19, 0
	s_cselect_b64 s[0:1], -1, 0
	s_and_b64 s[2:3], s[0:1], exec
	s_cselect_b32 s20, 0x220, s18
	s_mov_b32 s41, 0
	s_cmpk_lt_u32 s96, 0x100
	s_cbranch_scc1 .Ldqs4_go
	s_mov_b32 s41, 1
	v_writelane_b32 v245, s0, 0
	v_writelane_b32 v245, s1, 1
	v_writelane_b32 v245, s2, 2
	v_writelane_b32 v245, s3, 3
	v_writelane_b32 v245, s4, 4
	v_writelane_b32 v245, s5, 5
	v_writelane_b32 v245, s6, 6
	v_writelane_b32 v245, s7, 7
	v_writelane_b32 v245, s8, 8
	v_writelane_b32 v245, s9, 9
	v_writelane_b32 v245, s10, 10
	v_writelane_b32 v245, s11, 11
	v_writelane_b32 v245, s12, 12
	v_writelane_b32 v245, s13, 13
	v_writelane_b32 v245, s14, 14
	v_writelane_b32 v245, s15, 15
	v_writelane_b32 v245, s16, 16
	v_writelane_b32 v245, s17, 17
	v_writelane_b32 v245, s18, 18
	v_writelane_b32 v245, s19, 19
	v_writelane_b32 v245, s20, 20
	v_writelane_b32 v245, s21, 21
	v_writelane_b32 v245, s22, 22
	v_writelane_b32 v245, s23, 23
	s_branch .LBB0_751
.Ldqs4_go:
	s_cmp_ge_i32 s96, s20
	s_mov_b32 s3, 0
	s_cbranch_scc1 .LBB0_741
	v_lshrrev_b32_e32 v4, 3, v0
	v_xor_b32_e32 v6, v4, v0
	v_lshlrev_b32_e32 v5, 7, v4
	v_lshlrev_b32_e32 v6, 4, v6
	s_movk_i32 s2, 0x70
	v_lshrrev_b32_e32 v2, 4, v0
	v_and_or_b32 v112, v6, s2, v5
	v_and_b32_e32 v6, 7, v0
	v_readlane_b32 s68, v237, 35
	v_bfe_u32 v3, v0, 4, 2
	v_bitop3_b32 v2, v2, v6, 3 bitop3:0x6c
	v_readlane_b32 s80, v237, 47
	v_readlane_b32 s81, v237, 48
	v_lshlrev_b32_e32 v113, 4, v2
	v_bitop3_b32 v2, v3, v6, 4 bitop3:0x36
	v_readlane_b32 s82, v237, 49
	v_readlane_b32 s83, v237, 50
	s_mov_b64 s[24:25], s[80:81]
	v_lshrrev_b32_e32 v5, 1, v0
	v_lshlrev_b32_e32 v117, 4, v2
	v_and_b32_e32 v2, 64, v0
	v_lshlrev_b32_e32 v98, 10, v4
	v_mov_b32_e32 v99, 0
	s_mov_b64 s[26:27], s[82:83]
	v_lshlrev_b32_e32 v4, 4, v0
	v_and_or_b32 v114, v5, 64, v174
	v_and_or_b32 v118, v5, 24, v2
	v_lshl_add_u64 v[2:3], s[26:27], 0, v[98:99]
	v_and_b32_e32 v4, 0x70, v4
	v_mov_b32_e32 v5, v99
	v_lshl_add_u64 v[2:3], v[2:3], 0, v[4:5]
	s_mov_b64 s[4:5], 0x2400000
	v_lshl_add_u64 v[100:101], v[2:3], 0, s[4:5]
	v_lshl_add_u64 v[2:3], s[54:55], 0, v[98:99]
	v_lshl_add_u64 v[2:3], v[2:3], 0, v[4:5]
	s_mov_b64 s[4:5], 0xed80000
	v_lshlrev_b32_e32 v7, 7, v0
	v_lshl_add_u64 v[102:103], v[2:3], 0, s[4:5]
	v_lshlrev_b32_e32 v2, 4, v6
	s_movk_i32 s2, 0x7c00
	s_add_u32 s4, s54, 0xd580000
	v_and_or_b32 v98, v7, s2, v2
	v_lshlrev_b32_e32 v115, 7, v114
	v_and_b32_e32 v116, 0x2780, v7
	s_addc_u32 s5, s55, 0
	v_lshl_add_u64 v[104:105], s[26:27], 0, v[98:99]
	s_lshl_b32 s21, s96, 5
	s_lshl_b32 s22, s52, 5
	v_lshl_add_u64 v[106:107], s[54:55], 0, v[98:99]
	s_lshl_b32 s23, s96, 7
	s_lshl_b32 s24, s52, 7
	s_mov_b32 s25, 0x8000
	s_mov_b32 s26, 0x10000
	s_mov_b32 s27, 0x18000
	s_movk_i32 s28, 0x1c00
	s_mov_b64 s[6:7], 0x2200800
	s_mov_b32 s29, s96
	v_readlane_b32 s69, v237, 36
	v_readlane_b32 s70, v237, 37
	v_readlane_b32 s71, v237, 38
	v_readlane_b32 s72, v237, 39
	v_readlane_b32 s73, v237, 40
	v_readlane_b32 s74, v237, 41
	v_readlane_b32 s75, v237, 42
	v_readlane_b32 s76, v237, 43
	v_readlane_b32 s77, v237, 44
	v_readlane_b32 s78, v237, 45
	v_readlane_b32 s79, v237, 46
	s_branch .LBB0_733

.LBB0_751:
	s_cmp_eq_u32 s41, 2
	s_cbranch_scc1 .Ldqs4_done
	s_add_i32 s2, s52, 0xfffffeef
	s_sub_i32 s3, 0x220, s52
	s_cmpk_lt_u32 s2, 0x10f
	s_cselect_b32 s2, s3, 0
	s_and_b64 s[0:1], s[0:1], exec
	s_cselect_b32 s0, s2, s16
	s_cmp_lt_i32 s96, s0
	s_cbranch_scc1 .LBB0_756
	s_sub_i32 s1, s96, s0
	v_lshl_or_b32 v2, s1, 2, v171
	s_movk_i32 s1, 0x4400
	v_cmp_gt_u32_e32 vcc, s1, v2
	s_and_saveexec_b64 s[2:3], vcc
	s_cbranch_execz .LBB0_755
	v_mbcnt_lo_u32_b32 v3, -1, 0
	v_mbcnt_hi_u32_b32 v3, -1, v3
	v_and_b32_e32 v5, 64, v3
	v_xor_b32_e32 v4, 1, v3
	v_add_u32_e32 v5, 64, v5
	v_cmp_lt_i32_e32 vcc, v4, v5
	s_sub_i32 s6, s52, s0
	v_readlane_b32 s8, v237, 35
	v_cndmask_b32_e32 v4, v3, v4, vcc
	v_lshlrev_b32_e32 v10, 2, v4
	v_xor_b32_e32 v4, 2, v3
	v_cmp_lt_i32_e32 vcc, v4, v5
	s_lshl_b32 s4, s6, 2
	v_mov_b32_e32 v7, 0
	v_cndmask_b32_e32 v4, v3, v4, vcc
	v_lshlrev_b32_e32 v11, 2, v4
	v_xor_b32_e32 v4, 4, v3
	v_cmp_lt_i32_e32 vcc, v4, v5
	v_readlane_b32 s10, v237, 37
	v_readlane_b32 s11, v237, 38
	v_cndmask_b32_e32 v4, v3, v4, vcc
	v_lshlrev_b32_e32 v12, 2, v4
	v_xor_b32_e32 v4, 8, v3
	v_cmp_lt_i32_e32 vcc, v4, v5
	v_readlane_b32 s9, v237, 36
	v_readlane_b32 s12, v237, 39
	v_cndmask_b32_e32 v3, v3, v4, vcc
	v_lshlrev_b32_e32 v13, 2, v3
	v_lshlrev_b32_e32 v3, 5, v0
	v_and_b32_e32 v6, 0x1e0, v3
	v_ashrrev_i32_e32 v3, 31, v2
	v_readlane_b32 s13, v237, 40
	v_lshl_add_u64 v[4:5], s[10:11], 0, v[6:7]
	v_mov_b32_e32 v177, v7
	s_movk_i32 s0, 0x1c00
	v_mov_b64_e32 v[6:7], s[54:55]
	s_ashr_i32 s5, s4, 31
	v_lshlrev_b64 v[8:9], 10, v[2:3]
	v_mad_i64_i32 v[6:7], s[0:1], v2, s0, v[6:7]
	s_mulk_i32 s6, 0x7000
	s_mul_hi_i32 s7, s4, 0x1c00
	v_lshl_add_u64 v[8:9], s[54:55], 0, v[8:9]
	s_lshl_b64 s[8:9], s[4:5], 10
	s_mov_b64 s[10:11], 0
	s_mov_b32 s5, 0x2201000
	v_mov_b32_e32 v3, 0x358637bd
	s_mov_b32 s12, 0x800000
	s_movk_i32 s13, 0x43ff
	v_readlane_b32 s14, v237, 41
	v_readlane_b32 s15, v237, 42
	v_readlane_b32 s16, v237, 43
	v_readlane_b32 s17, v237, 44
	v_readlane_b32 s18, v237, 45
	v_readlane_b32 s19, v237, 46
	v_readlane_b32 s20, v237, 47
	v_readlane_b32 s21, v237, 48
	v_readlane_b32 s22, v237, 49
	v_readlane_b32 s23, v237, 50

.LBB0_756:
	s_cmp_lg_u32 s41, 1
	s_cbranch_scc1 .Ldqs4_done
	s_mov_b32 s41, 2
	v_readlane_b32 s0, v245, 0
	v_readlane_b32 s1, v245, 1
	v_readlane_b32 s2, v245, 2
	v_readlane_b32 s3, v245, 3
	v_readlane_b32 s4, v245, 4
	v_readlane_b32 s5, v245, 5
	v_readlane_b32 s6, v245, 6
	v_readlane_b32 s7, v245, 7
	v_readlane_b32 s8, v245, 8
	v_readlane_b32 s9, v245, 9
	v_readlane_b32 s10, v245, 10
	v_readlane_b32 s11, v245, 11
	v_readlane_b32 s12, v245, 12
	v_readlane_b32 s13, v245, 13
	v_readlane_b32 s14, v245, 14
	v_readlane_b32 s15, v245, 15
	v_readlane_b32 s16, v245, 16
	v_readlane_b32 s17, v245, 17
	v_readlane_b32 s18, v245, 18
	v_readlane_b32 s19, v245, 19
	v_readlane_b32 s20, v245, 20
	v_readlane_b32 s21, v245, 21
	v_readlane_b32 s22, v245, 22
	v_readlane_b32 s23, v245, 23
	s_nop 3
	s_branch .Ldqs4_go

.LBB0_1061:
	s_lshl_b32 s5, s59, 6
	s_lshl_b32 s4, s8, 7
	s_and_b32 s5, s5, 64
	s_or_b32 s4, s4, s5
	s_ashr_i32 s5, s4, 31
	s_lshl_b32 s6, s7, 7
	s_lshl_b64 s[8:9], s[4:5], 11
	s_add_u32 s8, s54, s8
	s_addc_u32 s9, s55, s9
	s_ashr_i32 s7, s6, 31
	s_lshl_b64 s[10:11], s[6:7], 11
	v_lshrrev_b32_e32 v8, 3, v0
	s_add_u32 s12, s54, s10
	v_lshlrev_b32_e32 v22, 11, v8
	v_mov_b32_e32 v23, 0
	v_lshlrev_b32_e32 v4, 4, v0
	s_addc_u32 s13, s55, s11
	s_waitcnt lgkmcnt(0)
	v_lshl_add_u64 v[2:3], s[8:9], 0, v[22:23]
	v_and_b32_e32 v4, 0x70, v4
	v_mov_b32_e32 v5, v23
	s_waitcnt vmcnt(9)
	v_lshl_add_u64 v[58:59], v[2:3], 0, v[4:5]
	v_lshl_add_u64 v[2:3], s[12:13], 0, v[22:23]
	s_mov_b32 s5, 0x10000
	v_lshl_add_u64 v[2:3], v[2:3], 0, v[4:5]
	v_add_co_u32_e32 v4, vcc, s5, v58
	s_mov_b32 s5, 0xf000000
	s_nop 0
	v_addc_co_u32_e32 v5, vcc, 0, v59, vcc
	s_barrier
	s_mov_b32 m0, s98
	v_lshl_add_u64 v[34:35], v[58:59], 0, v[238:239]
	global_load_lds_dwordx4 v[34:35], off
	s_add_u32 m0, s98, 0x1000
	v_lshl_add_u64 v[38:39], v[4:5], 0, v[238:239]
	global_load_lds_dwordx4 v[38:39], off
	v_add_co_u32_e32 v4, vcc, s5, v2
	s_mov_b32 s5, 0xf010000
	s_nop 0
	v_addc_co_u32_e32 v5, vcc, 0, v3, vcc
	v_add_co_u32_e32 v6, vcc, s5, v2
	s_mov_b32 s5, 0xf020000
	s_nop 0
	v_addc_co_u32_e32 v7, vcc, 0, v3, vcc
	s_add_u32 m0, s98, 0x4000
	v_lshl_add_u64 v[42:43], v[4:5], 0, v[238:239]
	global_load_lds_dwordx4 v[42:43], off
	s_add_u32 m0, s98, 0x5000
	v_lshl_add_u64 v[46:47], v[6:7], 0, v[238:239]
	global_load_lds_dwordx4 v[46:47], off
	v_add_co_u32_e32 v4, vcc, s5, v2
	s_mov_b32 s5, 0xf030000
	s_nop 0
	v_addc_co_u32_e32 v5, vcc, 0, v3, vcc
	v_add_co_u32_e32 v2, vcc, s5, v2
	v_lshlrev_b32_e32 v7, 8, v0
	s_nop 0
	v_addc_co_u32_e32 v3, vcc, 0, v3, vcc
	s_add_u32 m0, s98, 0x6000
	v_lshl_add_u64 v[50:51], v[4:5], 0, v[238:239]
	global_load_lds_dwordx4 v[50:51], off
	s_add_u32 m0, s98, 0x7000
	v_lshl_add_u64 v[54:55], v[2:3], 0, v[238:239]
	global_load_lds_dwordx4 v[54:55], off
	v_lshrrev_b32_e32 v2, 4, v0
	v_bfe_u32 v3, v0, 4, 2
	v_and_b32_e32 v4, 7, v0
	v_lshrrev_b32_e32 v5, 2, v0
	v_lshlrev_b32_e32 v6, 7, v0
	v_lshlrev_b32_e32 v9, 7, v8
	v_xor_b32_e32 v8, v8, v0
	v_and_b32_e32 v62, 32, v5
	v_bitop3_b32 v2, v2, v4, 3 bitop3:0x6c
	v_bitop3_b32 v3, v3, v4, 4 bitop3:0x36
	v_and_b32_e32 v5, 0xf800, v7
	v_lshlrev_b32_e32 v4, 4, v4
	s_movk_i32 s12, 0x70
	v_and_b32_e32 v64, 0x2780, v6
	v_lshlrev_b32_e32 v6, 4, v8
	v_and_or_b32 v63, v0, 15, v62
	v_add_u32_e32 v100, s4, v63
	v_lshlrev_b32_e32 v101, 2, v100
	v_lshlrev_b32_e32 v100, 11, v100
	v_lshrrev_b32_e32 v102, 1, v0
	v_and_b32_e32 v102, 24, v102
	v_and_b32_e32 v103, 64, v0
	v_or3_b32 v102, v102, v103, s6
	v_lshl_add_u32 v100, v102, 1, v100
	v_add_u32_e32 v102, 0x8000, v100
	s_add_u32 s34, s54, 0xaa00000
	s_addc_u32 s35, s55, 0
	v_lshlrev_b32_e32 v65, 4, v2
	v_lshlrev_b32_e32 v66, 4, v3
	v_or3_b32 v2, s10, v5, v4
	v_mov_b32_e32 v3, s11
	s_mov_b32 s7, 0
	s_mov_b64 s[8:9], 0
	s_mov_b32 s5, 0
	v_and_or_b32 v67, v6, s12, v9
	v_lshlrev_b32_e32 v68, 7, v63
	v_lshl_add_u64 v[60:61], s[54:55], 0, v[2:3]
	v_mov_b32_e32 v22, v23
	v_mov_b32_e32 v24, v23
	v_mov_b32_e32 v25, v23
	v_mov_b32_e32 v30, v23
	v_mov_b32_e32 v31, v23
	v_mov_b32_e32 v32, v23
	v_mov_b32_e32 v33, v23
	v_mov_b32_e32 v26, v23
	v_mov_b32_e32 v27, v23
	v_mov_b32_e32 v28, v23
	v_mov_b32_e32 v29, v23
	v_mov_b32_e32 v18, v23
	v_mov_b32_e32 v19, v23
	v_mov_b32_e32 v20, v23
	v_mov_b32_e32 v21, v23
	v_mov_b32_e32 v14, v23
	v_mov_b32_e32 v15, v23
	v_mov_b32_e32 v16, v23
	v_mov_b32_e32 v17, v23
	v_mov_b32_e32 v10, v23
	v_mov_b32_e32 v11, v23
	v_mov_b32_e32 v12, v23
	v_mov_b32_e32 v13, v23
	v_mov_b32_e32 v6, v23
	v_mov_b32_e32 v7, v23
	v_mov_b32_e32 v8, v23
	v_mov_b32_e32 v9, v23
	v_mov_b32_e32 v2, v23
	v_mov_b32_e32 v3, v23
	v_mov_b32_e32 v4, v23
	v_mov_b32_e32 v5, v23
	s_waitcnt lgkmcnt(0)
	s_add_u32 m0, s98, 0x8000
	v_lshl_add_u64 v[34:35], v[34:35], 0, v[242:243]
	global_load_lds_dwordx4 v[34:35], off
	s_add_u32 m0, s98, 0x9000
	v_lshl_add_u64 v[38:39], v[38:39], 0, v[242:243]
	global_load_lds_dwordx4 v[38:39], off
	s_mov_b32 s100, 0
	s_mov_b32 s101, 0x4000
	s_waitcnt vmcnt(2)
	s_barrier
	s_branch .LBB0_1063

.Ldqv_13:
	s_waitcnt vmcnt(10)

.Ldq_13_4:
	s_cmp_lg_u32 s5, 14
	s_cbranch_scc1 .Ldqz_n
	global_load_dword v136, v101, s[0:1]
	global_load_dwordx4 v[104:107], v100, s[34:35]
	global_load_dwordx4 v[108:111], v100, s[54:55]
	global_load_dwordx4 v[112:115], v100, s[54:55] offset:64
	global_load_dwordx4 v[116:119], v100, s[34:35] offset:64
	global_load_dwordx4 v[120:123], v102, s[54:55]
	global_load_dwordx4 v[124:127], v102, s[34:35]
	global_load_dwordx4 v[128:131], v102, s[54:55] offset:64
	global_load_dword v137, v101, s[0:1] offset:64
	global_load_dwordx4 v[132:135], v102, s[34:35] offset:64

.LBB0_1069:
	v_lshrrev_b32_e32 v36, 1, v0
	v_and_b32_e32 v35, 64, v0
	v_add_u32_e32 v34, s4, v63
	v_and_b32_e32 v36, 24, v36
	v_or3_b32 v36, v36, v35, s6
	v_ashrrev_i32_e32 v35, 31, v34
	v_lshl_add_u64 v[44:45], v[34:35], 2, s[0:1]
	s_add_u32 s8, s54, 0xaa00000
	s_addc_u32 s9, s55, 0
	v_lshlrev_b64 v[38:39], 11, v[34:35]
	v_ashrrev_i32_e32 v37, 31, v36
	v_lshl_add_u64 v[42:43], s[8:9], 0, v[38:39]
	v_lshlrev_b64 v[50:51], 1, v[36:37]
	v_lshl_add_u64 v[74:75], v[42:43], 0, v[50:51]
	v_lshl_add_u64 v[40:41], s[54:55], 0, v[38:39]
	v_lshl_add_u64 v[72:73], v[40:41], 0, v[50:51]
	v_or_b32_e32 v34, 16, v34
	v_ashrrev_i32_e32 v35, 31, v34
	v_lshlrev_b64 v[52:53], 11, v[34:35]
	v_lshl_add_u64 v[76:77], v[34:35], 2, s[0:1]
	v_lshl_add_u64 v[34:35], s[60:61], 0, v[38:39]
	v_lshl_add_u64 v[36:37], s[54:55], 0, v[52:53]
	v_lshl_add_u64 v[38:39], s[8:9], 0, v[52:53]
	v_lshl_add_u64 v[78:79], v[36:37], 0, v[50:51]
	v_lshl_add_u64 v[80:81], v[38:39], 0, v[50:51]
	v_lshl_add_u64 v[82:83], v[34:35], 0, v[50:51]
	v_mov_b32_e32 v84, 0x358637bd
	s_mov_b32 s5, 0x800000
	s_waitcnt vmcnt(0)
	v_mov_b32_e32 v63, v136
	v_mov_b32_e32 v58, v104
	v_mov_b32_e32 v59, v105
	v_mov_b32_e32 v60, v106
	v_mov_b32_e32 v61, v107
	v_mov_b32_e32 v54, v108
	v_mov_b32_e32 v55, v109
	v_mov_b32_e32 v56, v110
	v_mov_b32_e32 v57, v111
	v_mov_b32_e32 v64, v112
	v_mov_b32_e32 v65, v113
	v_mov_b32_e32 v66, v114
	v_mov_b32_e32 v67, v115
	v_mov_b32_e32 v68, v116
	v_mov_b32_e32 v69, v117
	v_mov_b32_e32 v70, v118
	v_mov_b32_e32 v71, v119
	v_mov_b32_e32 v42, v120
	v_mov_b32_e32 v43, v121
	v_mov_b32_e32 v44, v122
	v_mov_b32_e32 v45, v123
	v_mov_b32_e32 v46, v124
	v_mov_b32_e32 v47, v125
	v_mov_b32_e32 v48, v126
	v_mov_b32_e32 v49, v127
	v_mov_b32_e32 v34, v128
	v_mov_b32_e32 v35, v129
	v_mov_b32_e32 v36, v130
	v_mov_b32_e32 v37, v131
	v_mov_b32_e32 v85, v137
	v_mov_b32_e32 v38, v132
	v_mov_b32_e32 v39, v133
	v_mov_b32_e32 v40, v134
	v_mov_b32_e32 v41, v135
	v_fmamk_f32 v63, v63, 0x3a800000, v84
	v_mul_f32_e32 v72, 0x4b800000, v63
	v_cmp_gt_f32_e32 vcc, s5, v63
	s_waitcnt vmcnt(8)
	v_lshlrev_b32_e32 v78, 16, v60
	v_cndmask_b32_e32 v63, v63, v72, vcc
	v_rsq_f32_e32 v63, v63
	v_and_b32_e32 v79, 0xffff0000, v60
	s_waitcnt vmcnt(7)
	v_lshlrev_b32_e32 v72, 16, v54
	v_lshlrev_b32_e32 v74, 16, v58
	v_mul_f32_e32 v60, 0x45800000, v63
	v_cndmask_b32_e32 v60, v63, v60, vcc
	v_mul_f32_e32 v24, v24, v60
	v_mul_f32_e32 v25, v25, v60
	v_mul_f32_e32 v22, v22, v60
	v_mul_f32_e32 v23, v23, v60
	v_mul_f32_e32 v24, 0xbfb8aa3b, v24
	v_mul_f32_e32 v25, 0xbfb8aa3b, v25
	v_mul_f32_e32 v30, v30, v60
	v_mul_f32_e32 v31, v31, v60
	v_mul_f32_e32 v32, v32, v60
	v_mul_f32_e32 v33, v33, v60
	v_mul_f32_e32 v22, 0xbfb8aa3b, v22
	v_mul_f32_e32 v23, 0xbfb8aa3b, v23
	v_exp_f32_e32 v24, v24
	v_exp_f32_e32 v25, v25
	v_mul_f32_e32 v30, 0xbfb8aa3b, v30
	v_mul_f32_e32 v31, 0xbfb8aa3b, v31
	v_mul_f32_e32 v32, 0xbfb8aa3b, v32
	v_mul_f32_e32 v33, 0xbfb8aa3b, v33
	v_exp_f32_e32 v22, v22
	v_exp_f32_e32 v23, v23
	v_exp_f32_e32 v30, v30
	v_exp_f32_e32 v31, v31
	v_exp_f32_e32 v32, v32
	v_exp_f32_e32 v33, v33
	v_add_f32_e32 v24, 1.0, v24
	v_add_f32_e32 v25, 1.0, v25
	v_add_f32_e32 v22, 1.0, v22
	v_add_f32_e32 v23, 1.0, v23
	v_rcp_f32_e32 v24, v24
	v_rcp_f32_e32 v25, v25
	v_add_f32_e32 v30, 1.0, v30
	v_add_f32_e32 v31, 1.0, v31
	v_add_f32_e32 v32, 1.0, v32
	v_add_f32_e32 v33, 1.0, v33
	v_rcp_f32_e32 v22, v22
	v_rcp_f32_e32 v23, v23
	v_rcp_f32_e32 v30, v30
	v_rcp_f32_e32 v31, v31
	v_rcp_f32_e32 v32, v32
	v_rcp_f32_e32 v33, v33
	v_and_b32_e32 v73, 0xffff0000, v54
	v_and_b32_e32 v75, 0xffff0000, v58
	v_lshlrev_b32_e32 v54, 16, v55
	v_lshlrev_b32_e32 v58, 16, v59
	v_and_b32_e32 v55, 0xffff0000, v55
	v_and_b32_e32 v59, 0xffff0000, v59
	v_pk_fma_f32 v[24:25], v[24:25], v[58:59], v[54:55]
	v_lshlrev_b32_e32 v76, 16, v56
	v_and_b32_e32 v77, 0xffff0000, v56
	v_lshlrev_b32_e32 v56, 16, v57
	v_pk_fma_f32 v[72:73], v[22:23], v[74:75], v[72:73]
	v_cvt_pk_bf16_f32 v23, v24, v25
	v_pk_mul_f32 v[58:59], v[24:25], v[24:25]
	v_lshlrev_b32_e32 v24, 16, v61
	v_and_b32_e32 v57, 0xffff0000, v57
	v_and_b32_e32 v25, 0xffff0000, v61
	v_pk_fma_f32 v[30:31], v[30:31], v[78:79], v[76:77]
	v_pk_fma_f32 v[32:33], v[32:33], v[24:25], v[56:57]
	v_cvt_pk_bf16_f32 v22, v72, v73
	v_cvt_pk_bf16_f32 v24, v30, v31
	v_cvt_pk_bf16_f32 v25, v32, v33
	global_store_dwordx4 v[82:83], v[22:25], off
	v_mul_f32_e32 v18, v18, v60
	v_mul_f32_e32 v18, 0xbfb8aa3b, v18
	v_mul_f32_e32 v22, v26, v60
	v_mul_f32_e32 v22, 0xbfb8aa3b, v22
	v_exp_f32_e32 v23, v22
	v_mul_f32_e32 v22, v27, v60
	v_mul_f32_e32 v22, 0xbfb8aa3b, v22
	v_exp_f32_e32 v25, v22
	v_add_f32_e32 v23, 1.0, v23
	v_rcp_f32_e32 v24, v23
	s_waitcnt vmcnt(7)
	v_lshlrev_b32_e32 v22, 16, v64
	v_add_f32_e32 v23, 1.0, v25
	v_rcp_f32_e32 v25, v23
	s_waitcnt vmcnt(6)
	v_lshlrev_b32_e32 v26, 16, v68
	v_and_b32_e32 v23, 0xffff0000, v64
	v_and_b32_e32 v27, 0xffff0000, v68
	v_pk_fma_f32 v[24:25], v[24:25], v[26:27], v[22:23]
	v_mul_f32_e32 v22, v28, v60
	v_mul_f32_e32 v22, 0xbfb8aa3b, v22
	v_exp_f32_e32 v23, v22
	v_mul_f32_e32 v22, v29, v60
	v_mul_f32_e32 v22, 0xbfb8aa3b, v22
	v_exp_f32_e32 v27, v22
	v_add_f32_e32 v23, 1.0, v23
	v_rcp_f32_e32 v26, v23
	v_lshlrev_b32_e32 v22, 16, v65
	v_add_f32_e32 v23, 1.0, v27
	v_rcp_f32_e32 v27, v23
	v_lshlrev_b32_e32 v28, 16, v69
	v_and_b32_e32 v23, 0xffff0000, v65
	v_and_b32_e32 v29, 0xffff0000, v69
	v_pk_fma_f32 v[26:27], v[26:27], v[28:29], v[22:23]
	v_cvt_pk_bf16_f32 v22, v24, v25
	v_pk_mul_f32 v[28:29], v[24:25], v[24:25]
	v_exp_f32_e32 v24, v18
	v_mul_f32_e32 v18, v19, v60
	v_mul_f32_e32 v18, 0xbfb8aa3b, v18
	v_exp_f32_e32 v19, v18
	v_add_f32_e32 v24, 1.0, v24
	v_rcp_f32_e32 v24, v24
	v_mul_f32_e32 v20, v20, v60
	v_add_f32_e32 v19, 1.0, v19
	v_rcp_f32_e32 v25, v19
	v_lshlrev_b32_e32 v18, 16, v66
	v_lshlrev_b32_e32 v56, 16, v70
	v_and_b32_e32 v19, 0xffff0000, v66
	v_and_b32_e32 v57, 0xffff0000, v70
	v_mul_f32_e32 v20, 0xbfb8aa3b, v20
	v_pk_fma_f32 v[18:19], v[24:25], v[56:57], v[18:19]
	v_exp_f32_e32 v24, v20
	v_mul_f32_e32 v20, v21, v60
	v_mul_f32_e32 v20, 0xbfb8aa3b, v20
	v_exp_f32_e32 v21, v20
	v_add_f32_e32 v24, 1.0, v24
	v_rcp_f32_e32 v24, v24
	v_lshlrev_b32_e32 v20, 16, v67
	v_add_f32_e32 v21, 1.0, v21
	v_rcp_f32_e32 v25, v21
	v_lshlrev_b32_e32 v56, 16, v71
	v_and_b32_e32 v21, 0xffff0000, v67
	v_and_b32_e32 v57, 0xffff0000, v71
	v_pk_fma_f32 v[20:21], v[24:25], v[56:57], v[20:21]
	v_pk_mul_f32 v[54:55], v[72:73], v[72:73]
	v_pk_mul_f32 v[30:31], v[30:31], v[30:31]
	v_cvt_pk_bf16_f32 v23, v26, v27
	v_cvt_pk_bf16_f32 v24, v18, v19
	v_cvt_pk_bf16_f32 v25, v20, v21
	v_pk_mul_f32 v[32:33], v[32:33], v[32:33]
	global_store_dwordx4 v[82:83], v[22:25], off offset:64
	v_pk_mul_f32 v[18:19], v[18:19], v[18:19]
	s_waitcnt vmcnt(3)
	v_fmac_f32_e32 v84, 0x3a800000, v85
	v_add_f32_e32 v22, v30, v31
	v_add_f32_e32 v23, v54, v55
	v_add_f32_e32 v22, v32, v22
	v_add_f32_e32 v23, v58, v23
	v_add_f32_e32 v18, v18, v19
	v_mul_f32_e32 v19, 0x4b800000, v84
	v_cmp_gt_f32_e32 vcc, s5, v84
	v_add_f32_e32 v22, v33, v22
	v_add_f32_e32 v23, v59, v23
	v_cndmask_b32_e32 v19, v84, v19, vcc
	v_pk_mul_f32 v[26:27], v[26:27], v[26:27]
	v_add_f32_e32 v22, v23, v22
	v_add_f32_e32 v23, v28, v29
	v_rsq_f32_e32 v19, v19
	v_pk_mul_f32 v[20:21], v[20:21], v[20:21]
	v_add_f32_e32 v23, v26, v23
	v_add_f32_e32 v23, v27, v23
	v_add_f32_e32 v18, v20, v18
	v_add_f32_e32 v22, v23, v22
	v_add_f32_e32 v18, v21, v18
	v_add_f32_e32 v30, v18, v22
	v_mul_f32_e32 v18, 0x45800000, v19
	v_cndmask_b32_e32 v26, v19, v18, vcc
	v_mul_f32_e32 v14, v14, v26
	v_mul_f32_e32 v14, 0xbfb8aa3b, v14
	v_exp_f32_e32 v18, v14
	v_mul_f32_e32 v14, v15, v26
	v_mul_f32_e32 v14, 0xbfb8aa3b, v14
	v_exp_f32_e32 v15, v14
	v_add_f32_e32 v18, 1.0, v18
	v_rcp_f32_e32 v18, v18
	v_mul_f32_e32 v16, v16, v26
	v_add_f32_e32 v15, 1.0, v15
	v_rcp_f32_e32 v19, v15
	v_lshlrev_b32_e32 v14, 16, v42
	v_lshlrev_b32_e32 v22, 16, v46
	v_and_b32_e32 v15, 0xffff0000, v42
	v_and_b32_e32 v23, 0xffff0000, v46
	v_mul_f32_e32 v16, 0xbfb8aa3b, v16
	v_mul_f32_e32 v10, v10, v26
	v_lshl_add_u64 v[20:21], s[60:61], 0, v[52:53]
	v_pk_fma_f32 v[14:15], v[18:19], v[22:23], v[14:15]
	v_exp_f32_e32 v18, v16
	v_mul_f32_e32 v16, v17, v26
	v_mul_f32_e32 v10, 0xbfb8aa3b, v10
	v_mul_f32_e32 v16, 0xbfb8aa3b, v16
	v_lshl_add_u64 v[28:29], v[20:21], 0, v[50:51]
	v_exp_f32_e32 v20, v10
	v_mul_f32_e32 v10, v11, v26
	v_exp_f32_e32 v17, v16
	v_mul_f32_e32 v10, 0xbfb8aa3b, v10
	v_exp_f32_e32 v11, v10
	v_add_f32_e32 v18, 1.0, v18
	v_add_f32_e32 v17, 1.0, v17
	v_rcp_f32_e32 v18, v18
	v_rcp_f32_e32 v19, v17
	v_add_f32_e32 v20, 1.0, v20
	v_add_f32_e32 v11, 1.0, v11
	v_rcp_f32_e32 v20, v20
	v_rcp_f32_e32 v21, v11
	v_lshlrev_b32_e32 v16, 16, v43
	v_lshlrev_b32_e32 v22, 16, v47
	v_and_b32_e32 v17, 0xffff0000, v43
	v_and_b32_e32 v23, 0xffff0000, v47
	v_mul_f32_e32 v12, v12, v26
	v_pk_fma_f32 v[16:17], v[18:19], v[22:23], v[16:17]
	v_lshlrev_b32_e32 v10, 16, v44
	v_lshlrev_b32_e32 v22, 16, v48
	v_and_b32_e32 v11, 0xffff0000, v44
	v_and_b32_e32 v23, 0xffff0000, v48
	v_mul_f32_e32 v12, 0xbfb8aa3b, v12
	v_pk_fma_f32 v[10:11], v[20:21], v[22:23], v[10:11]
	v_exp_f32_e32 v20, v12
	v_mul_f32_e32 v12, v13, v26
	v_mul_f32_e32 v12, 0xbfb8aa3b, v12
	v_exp_f32_e32 v13, v12
	v_add_f32_e32 v20, 1.0, v20
	v_rcp_f32_e32 v20, v20
	v_lshlrev_b32_e32 v12, 16, v45
	v_add_f32_e32 v13, 1.0, v13
	v_rcp_f32_e32 v21, v13
	v_lshlrev_b32_e32 v22, 16, v49
	v_and_b32_e32 v13, 0xffff0000, v45
	v_and_b32_e32 v23, 0xffff0000, v49
	v_pk_fma_f32 v[12:13], v[20:21], v[22:23], v[12:13]
	v_mul_f32_e32 v6, v6, v26
	v_cvt_pk_bf16_f32 v18, v14, v15
	v_cvt_pk_bf16_f32 v19, v16, v17
	v_cvt_pk_bf16_f32 v20, v10, v11
	v_cvt_pk_bf16_f32 v21, v12, v13
	v_mul_f32_e32 v6, 0xbfb8aa3b, v6
	global_store_dwordx4 v[28:29], v[18:21], off
	v_mul_f32_e32 v8, v8, v26
	v_mul_f32_e32 v8, 0xbfb8aa3b, v8
	v_exp_f32_e32 v18, v6
	v_mul_f32_e32 v6, v7, v26
	v_mul_f32_e32 v6, 0xbfb8aa3b, v6
	v_exp_f32_e32 v7, v6
	v_add_f32_e32 v18, 1.0, v18
	v_rcp_f32_e32 v18, v18
	v_lshlrev_b32_e32 v6, 16, v34
	v_add_f32_e32 v7, 1.0, v7
	v_rcp_f32_e32 v19, v7
	s_waitcnt vmcnt(3)
	v_lshlrev_b32_e32 v20, 16, v38
	v_and_b32_e32 v7, 0xffff0000, v34
	v_and_b32_e32 v21, 0xffff0000, v38
	v_pk_fma_f32 v[6:7], v[18:19], v[20:21], v[6:7]
	v_exp_f32_e32 v18, v8
	v_mul_f32_e32 v8, v9, v26
	v_mul_f32_e32 v8, 0xbfb8aa3b, v8
	v_exp_f32_e32 v9, v8
	v_add_f32_e32 v18, 1.0, v18
	v_rcp_f32_e32 v18, v18
	v_mul_f32_e32 v2, v2, v26
	v_add_f32_e32 v9, 1.0, v9
	v_rcp_f32_e32 v19, v9
	v_lshlrev_b32_e32 v8, 16, v35
	v_lshlrev_b32_e32 v20, 16, v39
	v_and_b32_e32 v9, 0xffff0000, v35
	v_and_b32_e32 v21, 0xffff0000, v39
	v_mul_f32_e32 v2, 0xbfb8aa3b, v2
	v_pk_fma_f32 v[8:9], v[18:19], v[20:21], v[8:9]
	v_exp_f32_e32 v18, v2
	v_mul_f32_e32 v2, v3, v26
	v_mul_f32_e32 v2, 0xbfb8aa3b, v2
	v_exp_f32_e32 v3, v2
	v_add_f32_e32 v18, 1.0, v18
	v_rcp_f32_e32 v18, v18
	v_mul_f32_e32 v4, v4, v26
	v_add_f32_e32 v3, 1.0, v3
	v_rcp_f32_e32 v19, v3
	v_lshlrev_b32_e32 v2, 16, v36
	v_lshlrev_b32_e32 v20, 16, v40
	v_and_b32_e32 v3, 0xffff0000, v36
	v_and_b32_e32 v21, 0xffff0000, v40
	v_mul_f32_e32 v4, 0xbfb8aa3b, v4
	v_pk_fma_f32 v[2:3], v[18:19], v[20:21], v[2:3]
	v_exp_f32_e32 v18, v4
	v_mul_f32_e32 v4, v5, v26
	v_mul_f32_e32 v4, 0xbfb8aa3b, v4
	v_exp_f32_e32 v5, v4
	v_add_f32_e32 v18, 1.0, v18
	v_rcp_f32_e32 v18, v18
	v_lshlrev_b32_e32 v4, 16, v37
	v_add_f32_e32 v5, 1.0, v5
	v_rcp_f32_e32 v19, v5
	v_lshlrev_b32_e32 v20, 16, v41
	v_and_b32_e32 v5, 0xffff0000, v37
	v_and_b32_e32 v21, 0xffff0000, v41
	v_pk_fma_f32 v[4:5], v[18:19], v[20:21], v[4:5]
	v_mbcnt_lo_u32_b32 v18, -1, 0
	v_mbcnt_hi_u32_b32 v18, -1, v18
	v_and_b32_e32 v20, 64, v18
	v_xor_b32_e32 v19, 16, v18
	v_add_u32_e32 v21, 64, v20
	v_cmp_lt_i32_e32 vcc, v19, v21
	v_xor_b32_e32 v22, 32, v18
	v_cvt_pk_bf16_f32 v24, v6, v7
	v_cndmask_b32_e32 v19, v18, v19, vcc
	v_lshlrev_b32_e32 v20, 2, v19
	ds_bpermute_b32 v19, v20, v30
	v_cmp_lt_i32_e32 vcc, v22, v21
	v_cvt_pk_bf16_f32 v25, v8, v9
	v_cvt_pk_bf16_f32 v26, v2, v3
	v_cndmask_b32_e32 v18, v18, v22, vcc
	v_lshlrev_b32_e32 v21, 2, v18
	s_waitcnt lgkmcnt(0)
	v_add_f32_e32 v22, v30, v19
	ds_bpermute_b32 v23, v21, v22
	v_add3_u32 v18, v62, v1, s4
	v_cvt_pk_bf16_f32 v27, v4, v5
	v_cmp_gt_u32_e32 vcc, 16, v1
	v_ashrrev_i32_e32 v19, 31, v18
	global_store_dwordx4 v[28:29], v[24:27], off offset:64
	s_and_saveexec_b64 s[4:5], vcc
	s_cbranch_execz .LBB0_1071
	s_waitcnt lgkmcnt(0)
	v_add_f32_e32 v24, v22, v23
	v_lshl_add_u64 v[22:23], v[18:19], 2, s[2:3]
	global_atomic_add_f32 v[22:23], v24, off
